# Up epilogue: one unconditional wait after each conv-weight load batch instead of a vmcnt(0) in every token block (which drained the previous store)
# speedup vs baseline: 1.0273x; 1.0023x over previous
.LBB0_833:
	v_mbcnt_lo_u32_b32 v108, -1, 0
	v_mbcnt_hi_u32_b32 v108, -1, v108
	s_lshl_b32 s0, s4, 7
	v_readlane_b32 s1, v253, 44
	v_and_b32_e32 v162, 15, v108
	v_ashrrev_i32_e32 v108, 4, v108
	s_or_b32 s0, s0, s1
	s_mul_i32 s18, s12, 0xfc
	v_lshl_add_u32 v184, v108, 3, s0
	v_ashrrev_i32_e32 v185, 31, v184
	v_lshlrev_b64 v[120:121], 2, v[184:185]
	v_lshl_add_u64 v[186:187], s[24:25], 0, v[120:121]
	v_lshl_add_u64 v[108:109], s[28:29], 0, v[120:121]
	v_lshl_add_u64 v[110:111], s[30:31], 0, v[120:121]
	v_lshl_add_u64 v[188:189], s[26:27], 0, v[120:121]
	v_lshl_add_u64 v[116:117], s[34:35], 0, v[120:121]
	global_load_dwordx4 v[144:147], v[186:187], off
	global_load_dwordx4 v[140:143], v[108:109], off
	global_load_dwordx4 v[112:115], v[110:111], off
	v_lshl_add_u64 v[118:119], s[36:37], 0, v[120:121]
	global_load_dwordx4 v[108:111], v[188:189], off
	global_load_dwordx4 v[132:135], v[116:117], off
	global_load_dwordx4 v[128:131], v[118:119], off
	v_lshl_add_u64 v[116:117], s[40:41], 0, v[120:121]
	v_lshl_add_u64 v[120:121], s[42:43], 0, v[120:121]
	global_load_dwordx4 v[116:119], v[116:117], off
	v_readlane_b32 s0, v252, 48
	global_load_dwordx4 v[120:123], v[120:121], off
	s_mulk_i32 s0, 0x7e
	s_add_i32 s18, s18, s0
	s_add_i32 s0, s18, 0x7e
	v_lshl_add_u32 v221, v162, 3, s18
	s_min_i32 s19, s0, s66
	v_add_u32_e32 v222, -1, v221
	s_movk_i32 s0, 0x4000
	v_cmp_gt_i32_e32 vcc, s0, v222
	v_cmp_le_i32_e64 s[0:1], s18, v222
	v_cmp_gt_i32_e64 s[4:5], s19, v222
	v_cndmask_b32_e32 v162, v217, v218, vcc
	v_and_b32_e32 v162, v162, v221
	v_mov_b32_dpp v204, v68 row_shr:1 row_mask:0xf bank_mask:0xf bound_ctrl:1
	v_mov_b32_dpp v196, v156 row_shl:1 row_mask:0xf bank_mask:0xf bound_ctrl:1
	v_mov_b32_dpp v202, v64 row_shr:1 row_mask:0xf bank_mask:0xf bound_ctrl:1
	v_mov_b32_dpp v194, v152 row_shl:1 row_mask:0xf bank_mask:0xf bound_ctrl:1
	v_mov_b32_dpp v205, v69 row_shr:1 row_mask:0xf bank_mask:0xf bound_ctrl:1
	v_mov_b32_dpp v197, v157 row_shl:1 row_mask:0xf bank_mask:0xf bound_ctrl:1
	v_mov_b32_dpp v203, v65 row_shr:1 row_mask:0xf bank_mask:0xf bound_ctrl:1
	v_mov_b32_dpp v195, v153 row_shl:1 row_mask:0xf bank_mask:0xf bound_ctrl:1
	v_mov_b32_dpp v200, v70 row_shr:1 row_mask:0xf bank_mask:0xf bound_ctrl:1
	v_mov_b32_dpp v192, v158 row_shl:1 row_mask:0xf bank_mask:0xf bound_ctrl:1
	v_mov_b32_dpp v198, v66 row_shr:1 row_mask:0xf bank_mask:0xf bound_ctrl:1
	v_mov_b32_dpp v190, v154 row_shl:1 row_mask:0xf bank_mask:0xf bound_ctrl:1
	v_mov_b32_dpp v201, v71 row_shr:1 row_mask:0xf bank_mask:0xf bound_ctrl:1
	v_mov_b32_dpp v193, v159 row_shl:1 row_mask:0xf bank_mask:0xf bound_ctrl:1
	v_mov_b32_dpp v199, v67 row_shr:1 row_mask:0xf bank_mask:0xf bound_ctrl:1
	v_mov_b32_dpp v191, v155 row_shl:1 row_mask:0xf bank_mask:0xf bound_ctrl:1
	v_cmp_eq_u32_e32 vcc, 0, v162
	s_and_b64 s[50:51], s[0:1], s[4:5]
	s_waitcnt vmcnt(0)
	s_and_saveexec_b64 s[0:1], s[50:51]
	s_cbranch_execz .LBB0_835
	v_pk_mul_f32 v[172:173], v[156:157], v[140:141]
	v_cndmask_b32_e64 v167, v149, 0, vcc
	v_cndmask_b32_e64 v166, v148, 0, vcc
	v_pk_fma_f32 v[172:173], v[144:145], v[204:205], v[172:173]
	v_pk_mul_f32 v[206:207], v[152:153], v[128:129]
	v_pk_fma_f32 v[166:167], v[112:113], v[166:167], v[172:173]
	v_cndmask_b32_e64 v163, v137, 0, vcc
	v_pk_add_f32 v[166:167], v[108:109], v[166:167]
	v_cndmask_b32_e64 v162, v136, 0, vcc
	v_mul_f32_e32 v172, 0xbfb8aa3b, v166
	v_mul_f32_e32 v173, 0xbfb8aa3b, v167
	v_exp_f32_e32 v172, v172
	v_exp_f32_e32 v173, v173
	v_pk_fma_f32 v[202:203], v[132:133], v[202:203], v[206:207]
	v_pk_mul_f32 v[170:171], v[158:159], v[142:143]
	v_add_f32_e32 v172, 1.0, v172
	v_add_f32_e32 v173, 1.0, v173
	v_rcp_f32_e32 v172, v172
	v_rcp_f32_e32 v173, v173
	v_pk_fma_f32 v[162:163], v[116:117], v[162:163], v[202:203]
	v_cndmask_b32_e64 v169, v151, 0, vcc
	v_pk_add_f32 v[162:163], v[120:121], v[162:163]
	v_pk_mul_f32 v[166:167], v[166:167], v[172:173]
	v_cndmask_b32_e64 v168, v150, 0, vcc
	v_pk_mul_f32 v[162:163], v[162:163], v[166:167]
	v_pk_fma_f32 v[166:167], v[146:147], v[200:201], v[170:171]
	v_pk_mul_f32 v[204:205], v[154:155], v[130:131]
	v_pk_fma_f32 v[166:167], v[114:115], v[168:169], v[166:167]
	v_cndmask_b32_e64 v165, v139, 0, vcc
	v_pk_add_f32 v[166:167], v[110:111], v[166:167]
	v_cndmask_b32_e64 v164, v138, 0, vcc
	v_mul_f32_e32 v168, 0xbfb8aa3b, v166
	v_mul_f32_e32 v169, 0xbfb8aa3b, v167
	v_exp_f32_e32 v168, v168
	v_exp_f32_e32 v169, v169
	v_pk_fma_f32 v[170:171], v[134:135], v[198:199], v[204:205]
	v_readlane_b32 s4, v252, 52
	v_add_f32_e32 v168, 1.0, v168
	v_add_f32_e32 v169, 1.0, v169
	v_rcp_f32_e32 v168, v168
	v_rcp_f32_e32 v169, v169
	v_pk_fma_f32 v[164:165], v[118:119], v[164:165], v[170:171]
	v_readlane_b32 s5, v252, 53
	v_pk_add_f32 v[164:165], v[122:123], v[164:165]
	v_pk_mul_f32 v[166:167], v[166:167], v[168:169]
	v_cvt_pk_bf16_f32 v162, v162, v163
	v_pk_mul_f32 v[164:165], v[164:165], v[166:167]
	s_nop 0
	v_cvt_pk_bf16_f32 v163, v164, v165
	v_mov_b64_e32 v[164:165], s[4:5]
	s_movk_i32 s4, 0x1600
	v_mad_i64_i32 v[164:165], s[4:5], v222, s4, v[164:165]
	v_lshl_add_u64 v[164:165], v[184:185], 1, v[164:165]
	global_store_dwordx2 v[164:165], v[162:163], off
.LBB0_835:
	s_or_b64 exec, exec, s[0:1]
	s_movk_i32 s0, 0x4000
	v_cmp_gt_i32_e64 s[0:1], s0, v221
	v_cmp_le_i32_e64 s[4:5], s18, v221
	v_cmp_gt_i32_e64 s[6:7], s19, v221
	v_cndmask_b32_e64 v162, v217, v218, s[0:1]
	v_and_b32_e32 v162, v162, v221
	v_cmp_eq_u32_e64 s[0:1], 0, v162
	s_and_b64 s[52:53], s[4:5], s[6:7]
	s_and_saveexec_b64 s[4:5], s[52:53]
	s_cbranch_execz .LBB0_837
	v_cndmask_b32_e64 v157, v157, 0, s[0:1]
	v_cndmask_b32_e64 v156, v156, 0, s[0:1]
	v_pk_mul_f32 v[156:157], v[144:145], v[156:157]
	v_cndmask_b32_e64 v153, v153, 0, s[0:1]
	v_pk_fma_f32 v[156:157], v[148:149], v[140:141], v[156:157]
	v_cndmask_b32_e64 v152, v152, 0, s[0:1]
	v_pk_fma_f32 v[156:157], v[124:125], v[112:113], v[156:157]
	v_cndmask_b32_e64 v159, v159, 0, s[0:1]
	v_pk_add_f32 v[156:157], v[108:109], v[156:157]
	v_cndmask_b32_e64 v158, v158, 0, s[0:1]
	v_mul_f32_e32 v162, 0xbfb8aa3b, v156
	v_mul_f32_e32 v163, 0xbfb8aa3b, v157
	v_exp_f32_e32 v162, v162
	v_exp_f32_e32 v163, v163
	v_pk_mul_f32 v[158:159], v[146:147], v[158:159]
	v_pk_mul_f32 v[152:153], v[132:133], v[152:153]
	v_add_f32_e32 v162, 1.0, v162
	v_add_f32_e32 v163, 1.0, v163
	v_rcp_f32_e32 v162, v162
	v_rcp_f32_e32 v163, v163
	v_pk_fma_f32 v[158:159], v[150:151], v[142:143], v[158:159]
	v_pk_fma_f32 v[152:153], v[136:137], v[128:129], v[152:153]
	v_pk_fma_f32 v[158:159], v[126:127], v[114:115], v[158:159]
	v_pk_fma_f32 v[152:153], v[104:105], v[116:117], v[152:153]
	v_pk_add_f32 v[158:159], v[110:111], v[158:159]
	v_pk_add_f32 v[152:153], v[120:121], v[152:153]
	v_pk_mul_f32 v[156:157], v[156:157], v[162:163]
	v_cndmask_b32_e64 v155, v155, 0, s[0:1]
	v_pk_mul_f32 v[152:153], v[152:153], v[156:157]
	v_mul_f32_e32 v156, 0xbfb8aa3b, v158
	v_mul_f32_e32 v157, 0xbfb8aa3b, v159
	v_exp_f32_e32 v156, v156
	v_exp_f32_e32 v157, v157
	v_cndmask_b32_e64 v154, v154, 0, s[0:1]
	v_pk_mul_f32 v[154:155], v[134:135], v[154:155]
	v_add_f32_e32 v156, 1.0, v156
	v_add_f32_e32 v157, 1.0, v157
	v_rcp_f32_e32 v156, v156
	v_rcp_f32_e32 v157, v157
	v_pk_fma_f32 v[154:155], v[138:139], v[130:131], v[154:155]
	v_readlane_b32 s6, v252, 52
	v_pk_fma_f32 v[154:155], v[106:107], v[118:119], v[154:155]
	v_pk_mul_f32 v[156:157], v[158:159], v[156:157]
	v_pk_add_f32 v[154:155], v[122:123], v[154:155]
	v_readlane_b32 s7, v252, 53
	v_pk_mul_f32 v[154:155], v[154:155], v[156:157]
	v_cvt_pk_bf16_f32 v152, v152, v153
	v_cvt_pk_bf16_f32 v153, v154, v155
	v_mov_b64_e32 v[154:155], s[6:7]
	s_movk_i32 s6, 0x1600
	v_mad_i64_i32 v[154:155], s[6:7], v221, s6, v[154:155]
	v_lshl_add_u64 v[154:155], v[184:185], 1, v[154:155]
	global_store_dwordx2 v[154:155], v[152:153], off
.LBB0_837:
	s_or_b64 exec, exec, s[4:5]
	s_movk_i32 s4, 0x3ffe
	v_cmp_gt_i32_e64 s[4:5], s4, v222
	v_or_b32_e32 v153, 1, v221
	v_add_u32_e32 v152, 2, v221
	v_cndmask_b32_e64 v154, v217, v218, s[4:5]
	v_and_b32_e32 v154, v154, v152
	v_cmp_le_i32_e64 s[4:5], s18, v153
	v_cmp_gt_i32_e64 s[6:7], s19, v153
	v_cmp_eq_u32_e64 s[14:15], 0, v154
	s_and_b64 s[54:55], s[4:5], s[6:7]
	s_and_saveexec_b64 s[4:5], s[54:55]
	s_cbranch_execz .LBB0_839
	v_pk_mul_f32 v[166:167], v[124:125], v[140:141]
	v_cndmask_b32_e64 v163, v101, 0, s[14:15]
	v_cndmask_b32_e64 v162, v100, 0, s[14:15]
	v_pk_fma_f32 v[148:149], v[148:149], v[144:145], v[166:167]
	v_pk_mul_f32 v[164:165], v[126:127], v[142:143]
	v_pk_fma_f32 v[148:149], v[112:113], v[162:163], v[148:149]
	v_cndmask_b32_e64 v159, v103, 0, s[14:15]
	v_pk_add_f32 v[148:149], v[108:109], v[148:149]
	v_cndmask_b32_e64 v158, v102, 0, s[14:15]
	v_mul_f32_e32 v162, 0xbfb8aa3b, v148
	v_exp_f32_e32 v162, v162
	v_pk_fma_f32 v[150:151], v[150:151], v[146:147], v[164:165]
	v_pk_mul_f32 v[164:165], v[104:105], v[128:129]
	v_pk_fma_f32 v[150:151], v[114:115], v[158:159], v[150:151]
	v_add_f32_e32 v158, 1.0, v162
	v_pk_mul_f32 v[162:163], v[106:107], v[130:131]
	v_cndmask_b32_e64 v155, v99, 0, s[14:15]
	v_cndmask_b32_e64 v154, v98, 0, s[14:15]
	v_cndmask_b32_e64 v157, v97, 0, s[14:15]
	v_cndmask_b32_e64 v156, v96, 0, s[14:15]
	v_pk_add_f32 v[150:151], v[110:111], v[150:151]
	v_pk_fma_f32 v[138:139], v[138:139], v[134:135], v[162:163]
	v_pk_fma_f32 v[136:137], v[136:137], v[132:133], v[164:165]
	v_mul_f32_e32 v159, 0xbfb8aa3b, v149
	v_exp_f32_e32 v159, v159
	v_pk_fma_f32 v[136:137], v[116:117], v[156:157], v[136:137]
	v_pk_fma_f32 v[138:139], v[118:119], v[154:155], v[138:139]
	v_mul_f32_e32 v155, 0xbfb8aa3b, v150
	v_mul_f32_e32 v156, 0xbfb8aa3b, v151
	v_exp_f32_e32 v155, v155
	v_exp_f32_e32 v156, v156
	v_add_f32_e32 v154, 1.0, v159
	v_rcp_f32_e32 v158, v158
	v_rcp_f32_e32 v159, v154
	v_add_f32_e32 v154, 1.0, v155
	v_add_f32_e32 v155, 1.0, v156
	v_rcp_f32_e32 v154, v154
	v_rcp_f32_e32 v155, v155
	v_pk_add_f32 v[136:137], v[120:121], v[136:137]
	v_pk_mul_f32 v[148:149], v[148:149], v[158:159]
	v_pk_add_f32 v[138:139], v[122:123], v[138:139]
	v_pk_mul_f32 v[136:137], v[136:137], v[148:149]
	v_pk_mul_f32 v[148:149], v[150:151], v[154:155]
	v_readlane_b32 s6, v252, 52
	v_pk_mul_f32 v[138:139], v[138:139], v[148:149]
	v_readlane_b32 s7, v252, 53
	v_cvt_pk_bf16_f32 v136, v136, v137
	v_cvt_pk_bf16_f32 v137, v138, v139
	v_mov_b64_e32 v[138:139], s[6:7]
	s_movk_i32 s6, 0x1600
	v_mad_i64_i32 v[138:139], s[6:7], v153, s6, v[138:139]
	v_lshl_add_u64 v[138:139], v[184:185], 1, v[138:139]
	global_store_dwordx2 v[138:139], v[136:137], off
.LBB0_839:
	s_or_b64 exec, exec, s[4:5]
	s_movk_i32 s4, 0x3ffd
	v_cmp_gt_i32_e64 s[4:5], s4, v222
	v_cmp_le_i32_e64 s[6:7], s18, v152
	v_cmp_gt_i32_e64 s[8:9], s19, v152
	v_cndmask_b32_e64 v136, v217, v218, s[4:5]
	v_and_b32_e32 v136, v136, v152
	v_cmp_eq_u32_e64 s[4:5], 0, v136
	s_and_b64 s[56:57], s[6:7], s[8:9]
	s_and_saveexec_b64 s[6:7], s[56:57]
	s_cbranch_execz .LBB0_841
	v_cndmask_b32_e64 v125, v125, 0, s[4:5]
	v_cndmask_b32_e64 v124, v124, 0, s[4:5]
	v_pk_mul_f32 v[124:125], v[144:145], v[124:125]
	v_cndmask_b32_e64 v105, v105, 0, s[4:5]
	v_pk_fma_f32 v[124:125], v[100:101], v[140:141], v[124:125]
	v_cndmask_b32_e64 v104, v104, 0, s[4:5]
	v_pk_fma_f32 v[124:125], v[92:93], v[112:113], v[124:125]
	v_cndmask_b32_e64 v127, v127, 0, s[4:5]
	v_pk_add_f32 v[124:125], v[108:109], v[124:125]
	v_cndmask_b32_e64 v126, v126, 0, s[4:5]
	v_mul_f32_e32 v136, 0xbfb8aa3b, v124
	v_mul_f32_e32 v137, 0xbfb8aa3b, v125
	v_exp_f32_e32 v136, v136
	v_exp_f32_e32 v137, v137
	v_pk_mul_f32 v[126:127], v[146:147], v[126:127]
	v_pk_mul_f32 v[104:105], v[132:133], v[104:105]
	v_add_f32_e32 v136, 1.0, v136
	v_add_f32_e32 v137, 1.0, v137
	v_rcp_f32_e32 v136, v136
	v_rcp_f32_e32 v137, v137
	v_pk_fma_f32 v[126:127], v[102:103], v[142:143], v[126:127]
	v_pk_fma_f32 v[104:105], v[96:97], v[128:129], v[104:105]
	v_pk_fma_f32 v[126:127], v[94:95], v[114:115], v[126:127]
	v_pk_fma_f32 v[104:105], v[88:89], v[116:117], v[104:105]
	v_pk_add_f32 v[126:127], v[110:111], v[126:127]
	v_pk_add_f32 v[104:105], v[120:121], v[104:105]
	v_pk_mul_f32 v[124:125], v[124:125], v[136:137]
	v_cndmask_b32_e64 v107, v107, 0, s[4:5]
	v_pk_mul_f32 v[104:105], v[104:105], v[124:125]
	v_mul_f32_e32 v124, 0xbfb8aa3b, v126
	v_mul_f32_e32 v125, 0xbfb8aa3b, v127
	v_exp_f32_e32 v124, v124
	v_exp_f32_e32 v125, v125
	v_cndmask_b32_e64 v106, v106, 0, s[4:5]
	v_pk_mul_f32 v[106:107], v[134:135], v[106:107]
	v_add_f32_e32 v124, 1.0, v124
	v_add_f32_e32 v125, 1.0, v125
	v_rcp_f32_e32 v124, v124
	v_rcp_f32_e32 v125, v125
	v_pk_fma_f32 v[106:107], v[98:99], v[130:131], v[106:107]
	v_readlane_b32 s8, v252, 52
	v_pk_fma_f32 v[106:107], v[90:91], v[118:119], v[106:107]
	v_pk_mul_f32 v[124:125], v[126:127], v[124:125]
	v_pk_add_f32 v[106:107], v[122:123], v[106:107]
	v_readlane_b32 s9, v252, 53
	v_pk_mul_f32 v[106:107], v[106:107], v[124:125]
	v_cvt_pk_bf16_f32 v104, v104, v105
	v_cvt_pk_bf16_f32 v105, v106, v107
	v_mov_b64_e32 v[106:107], s[8:9]
	s_movk_i32 s8, 0x1600
	v_mad_i64_i32 v[106:107], s[8:9], v152, s8, v[106:107]
	v_lshl_add_u64 v[106:107], v[184:185], 1, v[106:107]
	global_store_dwordx2 v[106:107], v[104:105], off
.LBB0_841:
	s_or_b64 exec, exec, s[6:7]
	s_movk_i32 s6, 0x3ffc
	v_cmp_gt_i32_e64 s[6:7], s6, v222
	v_add_u32_e32 v126, 3, v221
	v_add_u32_e32 v124, 4, v221
	v_cndmask_b32_e64 v104, v217, v218, s[6:7]
	v_and_b32_e32 v104, v104, v124
	v_cmp_le_i32_e64 s[8:9], s18, v126
	v_cmp_gt_i32_e64 s[10:11], s19, v126
	v_cmp_eq_u32_e64 s[6:7], 0, v104
	s_and_b64 s[58:59], s[8:9], s[10:11]
	s_and_saveexec_b64 s[8:9], s[58:59]
	s_cbranch_execz .LBB0_843
	v_pk_mul_f32 v[150:151], v[92:93], v[140:141]
	v_cndmask_b32_e64 v139, v85, 0, s[6:7]
	v_cndmask_b32_e64 v138, v84, 0, s[6:7]
	v_pk_fma_f32 v[100:101], v[100:101], v[144:145], v[150:151]
	v_pk_mul_f32 v[148:149], v[94:95], v[142:143]
	v_pk_fma_f32 v[100:101], v[112:113], v[138:139], v[100:101]
	v_cndmask_b32_e64 v137, v87, 0, s[6:7]
	v_pk_add_f32 v[100:101], v[108:109], v[100:101]
	v_cndmask_b32_e64 v136, v86, 0, s[6:7]
	v_mul_f32_e32 v125, 0xbfb8aa3b, v100
	v_exp_f32_e32 v125, v125
	v_pk_fma_f32 v[102:103], v[102:103], v[146:147], v[148:149]
	v_pk_mul_f32 v[138:139], v[90:91], v[130:131]
	v_pk_fma_f32 v[102:103], v[114:115], v[136:137], v[102:103]
	v_add_f32_e32 v125, 1.0, v125
	v_pk_mul_f32 v[148:149], v[88:89], v[128:129]
	v_cndmask_b32_e64 v105, v83, 0, s[6:7]
	v_cndmask_b32_e64 v104, v82, 0, s[6:7]
	v_cndmask_b32_e64 v107, v81, 0, s[6:7]
	v_cndmask_b32_e64 v106, v80, 0, s[6:7]
	v_pk_add_f32 v[102:103], v[110:111], v[102:103]
	v_rcp_f32_e32 v136, v125
	v_pk_fma_f32 v[98:99], v[98:99], v[134:135], v[138:139]
	v_pk_fma_f32 v[96:97], v[96:97], v[132:133], v[148:149]
	v_mul_f32_e32 v125, 0xbfb8aa3b, v101
	v_exp_f32_e32 v125, v125
	v_pk_fma_f32 v[96:97], v[116:117], v[106:107], v[96:97]
	v_pk_fma_f32 v[98:99], v[118:119], v[104:105], v[98:99]
	v_mul_f32_e32 v105, 0xbfb8aa3b, v102
	v_mul_f32_e32 v106, 0xbfb8aa3b, v103
	v_exp_f32_e32 v105, v105
	v_exp_f32_e32 v106, v106
	v_add_f32_e32 v104, 1.0, v125
	v_rcp_f32_e32 v137, v104
	v_add_f32_e32 v104, 1.0, v105
	v_add_f32_e32 v105, 1.0, v106
	v_rcp_f32_e32 v104, v104
	v_rcp_f32_e32 v105, v105
	v_pk_add_f32 v[96:97], v[120:121], v[96:97]
	v_pk_mul_f32 v[100:101], v[100:101], v[136:137]
	v_pk_add_f32 v[98:99], v[122:123], v[98:99]
	v_pk_mul_f32 v[96:97], v[96:97], v[100:101]
	v_pk_mul_f32 v[100:101], v[102:103], v[104:105]
	v_readlane_b32 s10, v252, 52
	v_pk_mul_f32 v[98:99], v[98:99], v[100:101]
	v_readlane_b32 s11, v252, 53
	v_cvt_pk_bf16_f32 v96, v96, v97
	v_cvt_pk_bf16_f32 v97, v98, v99
	v_mov_b64_e32 v[98:99], s[10:11]
	s_movk_i32 s10, 0x1600
	v_mad_i64_i32 v[98:99], s[10:11], v126, s10, v[98:99]
	v_lshl_add_u64 v[98:99], v[184:185], 1, v[98:99]
	global_store_dwordx2 v[98:99], v[96:97], off
.LBB0_843:
	s_or_b64 exec, exec, s[8:9]
	s_movk_i32 s8, 0x3ffb
	v_cmp_gt_i32_e64 s[8:9], s8, v222
	v_cmp_le_i32_e64 s[10:11], s18, v124
	v_cmp_gt_i32_e64 s[12:13], s19, v124
	v_cndmask_b32_e64 v96, v217, v218, s[8:9]
	v_and_b32_e32 v96, v96, v124
	v_cmp_eq_u32_e64 s[8:9], 0, v96
	s_and_b64 s[60:61], s[10:11], s[12:13]
	s_and_saveexec_b64 s[10:11], s[60:61]
	s_cbranch_execz .LBB0_845
	v_cndmask_b32_e64 v93, v93, 0, s[8:9]
	v_cndmask_b32_e64 v92, v92, 0, s[8:9]
	v_pk_mul_f32 v[92:93], v[144:145], v[92:93]
	v_cndmask_b32_e64 v89, v89, 0, s[8:9]
	v_pk_fma_f32 v[92:93], v[84:85], v[140:141], v[92:93]
	v_cndmask_b32_e64 v88, v88, 0, s[8:9]
	v_pk_fma_f32 v[92:93], v[76:77], v[112:113], v[92:93]
	v_cndmask_b32_e64 v95, v95, 0, s[8:9]
	v_pk_add_f32 v[92:93], v[108:109], v[92:93]
	v_cndmask_b32_e64 v94, v94, 0, s[8:9]
	v_mul_f32_e32 v96, 0xbfb8aa3b, v92
	v_mul_f32_e32 v97, 0xbfb8aa3b, v93
	v_exp_f32_e32 v96, v96
	v_exp_f32_e32 v97, v97
	v_pk_mul_f32 v[94:95], v[146:147], v[94:95]
	v_pk_mul_f32 v[88:89], v[132:133], v[88:89]
	v_add_f32_e32 v96, 1.0, v96
	v_add_f32_e32 v97, 1.0, v97
	v_rcp_f32_e32 v96, v96
	v_rcp_f32_e32 v97, v97
	v_pk_fma_f32 v[94:95], v[86:87], v[142:143], v[94:95]
	v_pk_fma_f32 v[88:89], v[80:81], v[128:129], v[88:89]
	v_pk_fma_f32 v[94:95], v[78:79], v[114:115], v[94:95]
	v_pk_fma_f32 v[88:89], v[72:73], v[116:117], v[88:89]
	v_pk_add_f32 v[94:95], v[110:111], v[94:95]
	v_pk_add_f32 v[88:89], v[120:121], v[88:89]
	v_pk_mul_f32 v[92:93], v[92:93], v[96:97]
	v_cndmask_b32_e64 v91, v91, 0, s[8:9]
	v_pk_mul_f32 v[88:89], v[88:89], v[92:93]
	v_mul_f32_e32 v92, 0xbfb8aa3b, v94
	v_mul_f32_e32 v93, 0xbfb8aa3b, v95
	v_exp_f32_e32 v92, v92
	v_exp_f32_e32 v93, v93
	v_cndmask_b32_e64 v90, v90, 0, s[8:9]
	v_pk_mul_f32 v[90:91], v[134:135], v[90:91]
	v_add_f32_e32 v92, 1.0, v92
	v_add_f32_e32 v93, 1.0, v93
	v_rcp_f32_e32 v92, v92
	v_rcp_f32_e32 v93, v93
	v_pk_fma_f32 v[90:91], v[82:83], v[130:131], v[90:91]
	v_readlane_b32 s12, v252, 52
	v_pk_fma_f32 v[90:91], v[74:75], v[118:119], v[90:91]
	v_pk_mul_f32 v[92:93], v[94:95], v[92:93]
	v_pk_add_f32 v[90:91], v[122:123], v[90:91]
	v_readlane_b32 s13, v252, 53
	v_pk_mul_f32 v[90:91], v[90:91], v[92:93]
	v_cvt_pk_bf16_f32 v88, v88, v89
	v_cvt_pk_bf16_f32 v89, v90, v91
	v_mov_b64_e32 v[90:91], s[12:13]
	s_movk_i32 s12, 0x1600
	v_mad_i64_i32 v[90:91], s[12:13], v124, s12, v[90:91]
	v_lshl_add_u64 v[90:91], v[184:185], 1, v[90:91]
	global_store_dwordx2 v[90:91], v[88:89], off
.LBB0_845:
	s_or_b64 exec, exec, s[10:11]
	s_movk_i32 s10, 0x3ffa
	v_cmp_gt_i32_e64 s[10:11], s10, v222
	v_add_u32_e32 v127, 5, v221
	v_add_u32_e32 v125, 6, v221
	v_cndmask_b32_e64 v88, v217, v218, s[10:11]
	v_and_b32_e32 v88, v88, v125
	v_cmp_le_i32_e64 s[12:13], s18, v127
	v_cmp_gt_i32_e64 s[16:17], s19, v127
	v_cmp_eq_u32_e64 s[10:11], 0, v88
	s_and_b64 s[62:63], s[12:13], s[16:17]
	s_and_saveexec_b64 s[12:13], s[62:63]
	s_cbranch_execz .LBB0_847
	v_pk_mul_f32 v[98:99], v[76:77], v[140:141]
	v_cndmask_b32_e64 v95, v69, 0, s[10:11]
	v_cndmask_b32_e64 v94, v68, 0, s[10:11]
	v_pk_fma_f32 v[84:85], v[84:85], v[144:145], v[98:99]
	v_pk_mul_f32 v[96:97], v[78:79], v[142:143]
	v_pk_fma_f32 v[84:85], v[112:113], v[94:95], v[84:85]
	v_cndmask_b32_e64 v93, v71, 0, s[10:11]
	v_pk_add_f32 v[84:85], v[108:109], v[84:85]
	v_cndmask_b32_e64 v92, v70, 0, s[10:11]
	v_mul_f32_e32 v94, 0xbfb8aa3b, v84
	v_exp_f32_e32 v94, v94
	v_pk_fma_f32 v[86:87], v[86:87], v[146:147], v[96:97]
	v_pk_mul_f32 v[96:97], v[72:73], v[128:129]
	v_pk_fma_f32 v[86:87], v[114:115], v[92:93], v[86:87]
	v_add_f32_e32 v92, 1.0, v94
	v_pk_mul_f32 v[94:95], v[74:75], v[130:131]
	v_cndmask_b32_e64 v89, v67, 0, s[10:11]
	v_cndmask_b32_e64 v88, v66, 0, s[10:11]
	v_cndmask_b32_e64 v91, v65, 0, s[10:11]
	v_cndmask_b32_e64 v90, v64, 0, s[10:11]
	v_pk_add_f32 v[86:87], v[110:111], v[86:87]
	v_pk_fma_f32 v[82:83], v[82:83], v[134:135], v[94:95]
	v_pk_fma_f32 v[80:81], v[80:81], v[132:133], v[96:97]
	v_mul_f32_e32 v93, 0xbfb8aa3b, v85
	v_exp_f32_e32 v93, v93
	v_pk_fma_f32 v[80:81], v[116:117], v[90:91], v[80:81]
	v_pk_fma_f32 v[82:83], v[118:119], v[88:89], v[82:83]
	v_mul_f32_e32 v89, 0xbfb8aa3b, v86
	v_mul_f32_e32 v90, 0xbfb8aa3b, v87
	v_exp_f32_e32 v89, v89
	v_exp_f32_e32 v90, v90
	v_add_f32_e32 v88, 1.0, v93
	v_rcp_f32_e32 v92, v92
	v_rcp_f32_e32 v93, v88
	v_add_f32_e32 v88, 1.0, v89
	v_add_f32_e32 v89, 1.0, v90
	v_rcp_f32_e32 v88, v88
	v_rcp_f32_e32 v89, v89
	v_pk_add_f32 v[80:81], v[120:121], v[80:81]
	v_pk_mul_f32 v[84:85], v[84:85], v[92:93]
	v_pk_add_f32 v[82:83], v[122:123], v[82:83]
	v_pk_mul_f32 v[80:81], v[80:81], v[84:85]
	v_pk_mul_f32 v[84:85], v[86:87], v[88:89]
	v_readlane_b32 s16, v252, 52
	v_pk_mul_f32 v[82:83], v[82:83], v[84:85]
	v_readlane_b32 s17, v252, 53
	v_cvt_pk_bf16_f32 v80, v80, v81
	v_cvt_pk_bf16_f32 v81, v82, v83
	v_mov_b64_e32 v[82:83], s[16:17]
	s_movk_i32 s16, 0x1600
	v_mad_i64_i32 v[82:83], s[16:17], v127, s16, v[82:83]
	v_lshl_add_u64 v[82:83], v[184:185], 1, v[82:83]
	global_store_dwordx2 v[82:83], v[80:81], off
.LBB0_847:
	s_or_b64 exec, exec, s[12:13]
	s_movk_i32 s12, 0x3ff9
	v_cmp_gt_i32_e64 s[12:13], s12, v222
	v_cmp_le_i32_e64 s[16:17], s18, v125
	v_cmp_gt_i32_e64 s[18:19], s19, v125
	v_cndmask_b32_e64 v80, v217, v218, s[12:13]
	v_and_b32_e32 v80, v80, v125
	v_cmp_eq_u32_e64 s[12:13], 0, v80
	s_and_b64 s[16:17], s[16:17], s[18:19]
	s_and_saveexec_b64 s[18:19], s[16:17]
	s_cbranch_execz .LBB0_849
	v_cndmask_b32_e64 v77, v77, 0, s[12:13]
	v_cndmask_b32_e64 v76, v76, 0, s[12:13]
	v_pk_mul_f32 v[76:77], v[144:145], v[76:77]
	v_cndmask_b32_e64 v73, v73, 0, s[12:13]
	v_pk_fma_f32 v[68:69], v[68:69], v[140:141], v[76:77]
	v_cndmask_b32_e64 v72, v72, 0, s[12:13]
	v_pk_fma_f32 v[68:69], v[112:113], v[196:197], v[68:69]
	v_pk_mul_f32 v[72:73], v[132:133], v[72:73]
	v_pk_add_f32 v[68:69], v[108:109], v[68:69]
	v_pk_fma_f32 v[64:65], v[64:65], v[128:129], v[72:73]
	v_mul_f32_e32 v76, 0xbfb8aa3b, v68
	v_mul_f32_e32 v72, 0xbfb8aa3b, v69
	v_exp_f32_e32 v76, v76
	v_exp_f32_e32 v72, v72
	v_cndmask_b32_e64 v79, v79, 0, s[12:13]
	v_cndmask_b32_e64 v78, v78, 0, s[12:13]
	v_add_f32_e32 v76, 1.0, v76
	v_add_f32_e32 v72, 1.0, v72
	v_rcp_f32_e32 v76, v76
	v_rcp_f32_e32 v77, v72
	v_pk_mul_f32 v[78:79], v[146:147], v[78:79]
	v_pk_fma_f32 v[64:65], v[116:117], v[194:195], v[64:65]
	v_pk_fma_f32 v[70:71], v[70:71], v[142:143], v[78:79]
	v_pk_add_f32 v[64:65], v[120:121], v[64:65]
	v_pk_mul_f32 v[68:69], v[68:69], v[76:77]
	v_cndmask_b32_e64 v75, v75, 0, s[12:13]
	v_pk_mul_f32 v[64:65], v[64:65], v[68:69]
	v_pk_fma_f32 v[68:69], v[114:115], v[192:193], v[70:71]
	v_cndmask_b32_e64 v74, v74, 0, s[12:13]
	v_pk_add_f32 v[68:69], v[110:111], v[68:69]
	v_pk_mul_f32 v[74:75], v[134:135], v[74:75]
	v_mul_f32_e32 v70, 0xbfb8aa3b, v68
	v_mul_f32_e32 v71, 0xbfb8aa3b, v69
	v_exp_f32_e32 v70, v70
	v_exp_f32_e32 v71, v71
	v_pk_fma_f32 v[66:67], v[66:67], v[130:131], v[74:75]
	v_readlane_b32 s84, v252, 52
	v_add_f32_e32 v70, 1.0, v70
	v_add_f32_e32 v71, 1.0, v71
	v_rcp_f32_e32 v70, v70
	v_rcp_f32_e32 v71, v71
	v_pk_fma_f32 v[66:67], v[118:119], v[190:191], v[66:67]
	v_readlane_b32 s85, v252, 53
	v_pk_add_f32 v[66:67], v[122:123], v[66:67]
	v_pk_mul_f32 v[68:69], v[68:69], v[70:71]
	v_cvt_pk_bf16_f32 v64, v64, v65
	v_pk_mul_f32 v[66:67], v[66:67], v[68:69]
	s_movk_i32 s45, 0x1600
	v_cvt_pk_bf16_f32 v65, v66, v67
	v_mov_b64_e32 v[66:67], s[84:85]
	v_mad_i64_i32 v[66:67], s[84:85], v125, s45, v[66:67]
	v_lshl_add_u64 v[66:67], v[184:185], 1, v[66:67]
	global_store_dwordx2 v[66:67], v[64:65], off
.LBB0_849:
	s_or_b64 exec, exec, s[18:19]
	v_or_b32_e32 v64, 4, v184
	v_ashrrev_i32_e32 v65, 31, v64
	v_lshlrev_b64 v[76:77], 2, v[64:65]
	v_lshl_add_u64 v[64:65], s[28:29], 0, v[76:77]
	v_lshl_add_u64 v[66:67], s[30:31], 0, v[76:77]
	v_lshl_add_u64 v[72:73], s[34:35], 0, v[76:77]
	global_load_dwordx4 v[88:91], v[186:187], off offset:16
	global_load_dwordx4 v[92:95], v[64:65], off
	global_load_dwordx4 v[68:71], v[66:67], off
	s_nop 0
	global_load_dwordx4 v[64:67], v[188:189], off offset:16
	v_lshl_add_u64 v[74:75], s[36:37], 0, v[76:77]
	global_load_dwordx4 v[80:83], v[72:73], off
	global_load_dwordx4 v[84:87], v[74:75], off
	v_lshl_add_u64 v[72:73], s[40:41], 0, v[76:77]
	v_lshl_add_u64 v[76:77], s[42:43], 0, v[76:77]
	global_load_dwordx4 v[72:75], v[72:73], off
	s_waitcnt vmcnt(0)
	v_mov_b32_dpp v110, v8 row_shr:1 row_mask:0xf bank_mask:0xf bound_ctrl:1
	global_load_dwordx4 v[76:79], v[76:77], off
	v_mov_b32_dpp v102, v60 row_shl:1 row_mask:0xf bank_mask:0xf bound_ctrl:1
	v_mov_b32_dpp v108, v0 row_shr:1 row_mask:0xf bank_mask:0xf bound_ctrl:1
	v_mov_b32_dpp v100, v56 row_shl:1 row_mask:0xf bank_mask:0xf bound_ctrl:1
	v_mov_b32_dpp v111, v9 row_shr:1 row_mask:0xf bank_mask:0xf bound_ctrl:1
	v_mov_b32_dpp v103, v61 row_shl:1 row_mask:0xf bank_mask:0xf bound_ctrl:1
	v_mov_b32_dpp v109, v1 row_shr:1 row_mask:0xf bank_mask:0xf bound_ctrl:1
	v_mov_b32_dpp v101, v57 row_shl:1 row_mask:0xf bank_mask:0xf bound_ctrl:1
	v_mov_b32_dpp v106, v10 row_shr:1 row_mask:0xf bank_mask:0xf bound_ctrl:1
	v_mov_b32_dpp v98, v62 row_shl:1 row_mask:0xf bank_mask:0xf bound_ctrl:1
	v_mov_b32_dpp v104, v2 row_shr:1 row_mask:0xf bank_mask:0xf bound_ctrl:1
	v_mov_b32_dpp v96, v58 row_shl:1 row_mask:0xf bank_mask:0xf bound_ctrl:1
	v_mov_b32_dpp v107, v11 row_shr:1 row_mask:0xf bank_mask:0xf bound_ctrl:1
	v_mov_b32_dpp v99, v63 row_shl:1 row_mask:0xf bank_mask:0xf bound_ctrl:1
	v_mov_b32_dpp v105, v3 row_shr:1 row_mask:0xf bank_mask:0xf bound_ctrl:1
	v_mov_b32_dpp v97, v59 row_shl:1 row_mask:0xf bank_mask:0xf bound_ctrl:1
	s_waitcnt vmcnt(0)
	s_and_saveexec_b64 s[18:19], s[50:51]
	s_cbranch_execnz .LBB0_858
	s_or_b64 exec, exec, s[18:19]
	s_and_saveexec_b64 s[18:19], s[52:53]
	s_cbranch_execnz .LBB0_859

.LBB0_858:
	v_pk_mul_f32 v[122:123], v[60:61], v[92:93]
	v_cndmask_b32_e64 v117, v53, 0, vcc
	v_cndmask_b32_e64 v116, v52, 0, vcc
	v_pk_fma_f32 v[110:111], v[88:89], v[110:111], v[122:123]
	v_pk_mul_f32 v[128:129], v[56:57], v[84:85]
	v_pk_fma_f32 v[110:111], v[116:117], v[68:69], v[110:111]
	v_cndmask_b32_e64 v113, v49, 0, vcc
	v_cndmask_b32_e64 v112, v48, 0, vcc
	v_pk_add_f32 v[110:111], v[64:65], v[110:111]
	v_pk_fma_f32 v[108:109], v[80:81], v[108:109], v[128:129]
	v_mul_f32_e32 v116, 0xbfb8aa3b, v110
	v_pk_fma_f32 v[108:109], v[112:113], v[72:73], v[108:109]
	v_mul_f32_e32 v112, 0xbfb8aa3b, v111
	v_exp_f32_e32 v116, v116
	v_exp_f32_e32 v112, v112
	v_pk_mul_f32 v[120:121], v[62:63], v[94:95]
	v_cndmask_b32_e64 v119, v55, 0, vcc
	v_add_f32_e32 v116, 1.0, v116
	v_add_f32_e32 v112, 1.0, v112
	v_rcp_f32_e32 v116, v116
	v_rcp_f32_e32 v117, v112
	v_cndmask_b32_e64 v118, v54, 0, vcc
	v_pk_fma_f32 v[106:107], v[90:91], v[106:107], v[120:121]
	v_pk_add_f32 v[108:109], v[76:77], v[108:109]
	v_pk_fma_f32 v[106:107], v[118:119], v[70:71], v[106:107]
	v_pk_mul_f32 v[110:111], v[110:111], v[116:117]
	v_pk_add_f32 v[106:107], v[66:67], v[106:107]
	v_pk_mul_f32 v[108:109], v[108:109], v[110:111]
	v_mul_f32_e32 v110, 0xbfb8aa3b, v106
	v_mul_f32_e32 v111, 0xbfb8aa3b, v107
	v_exp_f32_e32 v110, v110
	v_exp_f32_e32 v111, v111
	v_pk_mul_f32 v[122:123], v[58:59], v[86:87]
	v_cndmask_b32_e64 v115, v51, 0, vcc
	v_add_f32_e32 v110, 1.0, v110
	v_add_f32_e32 v111, 1.0, v111
	v_rcp_f32_e32 v110, v110
	v_rcp_f32_e32 v111, v111
	v_cndmask_b32_e64 v114, v50, 0, vcc
	v_pk_fma_f32 v[104:105], v[82:83], v[104:105], v[122:123]
	v_readlane_b32 s50, v252, 52
	v_pk_fma_f32 v[104:105], v[114:115], v[74:75], v[104:105]
	v_pk_mul_f32 v[106:107], v[106:107], v[110:111]
	v_pk_add_f32 v[104:105], v[78:79], v[104:105]
	v_readlane_b32 s51, v252, 53
	v_pk_mul_f32 v[104:105], v[104:105], v[106:107]
	s_movk_i32 s45, 0x1600
	v_cvt_pk_bf16_f32 v107, v104, v105
	v_mov_b64_e32 v[104:105], s[50:51]
	v_mad_i64_i32 v[104:105], s[50:51], v222, s45, v[104:105]
	v_cvt_pk_bf16_f32 v106, v108, v109
	v_lshl_add_u64 v[104:105], v[184:185], 1, v[104:105]
	global_store_dwordx2 v[104:105], v[106:107], off offset:8
	s_or_b64 exec, exec, s[18:19]
	s_and_saveexec_b64 s[18:19], s[52:53]
	s_cbranch_execz .LBB0_851
.LBB0_859:
	v_cndmask_b32_e64 v61, v61, 0, s[0:1]
	v_cndmask_b32_e64 v60, v60, 0, s[0:1]
	v_pk_mul_f32 v[106:107], v[52:53], v[92:93]
	v_cndmask_b32_e64 v63, v63, 0, s[0:1]
	v_pk_fma_f32 v[60:61], v[60:61], v[88:89], v[106:107]
	v_cndmask_b32_e64 v62, v62, 0, s[0:1]
	v_pk_fma_f32 v[60:61], v[44:45], v[68:69], v[60:61]
	v_pk_mul_f32 v[104:105], v[54:55], v[94:95]
	v_pk_add_f32 v[60:61], v[64:65], v[60:61]
	v_pk_fma_f32 v[62:63], v[62:63], v[90:91], v[104:105]
	v_mul_f32_e32 v106, 0xbfb8aa3b, v60
	v_exp_f32_e32 v106, v106
	v_pk_fma_f32 v[62:63], v[46:47], v[70:71], v[62:63]
	v_cndmask_b32_e64 v59, v59, 0, s[0:1]
	v_cndmask_b32_e64 v58, v58, 0, s[0:1]
	v_pk_add_f32 v[62:63], v[66:67], v[62:63]
	v_add_f32_e32 v104, 1.0, v106
	v_pk_mul_f32 v[106:107], v[50:51], v[86:87]
	v_mul_f32_e32 v105, 0xbfb8aa3b, v61
	v_pk_fma_f32 v[58:59], v[58:59], v[82:83], v[106:107]
	v_exp_f32_e32 v105, v105
	v_mul_f32_e32 v106, 0xbfb8aa3b, v62
	v_mul_f32_e32 v107, 0xbfb8aa3b, v63
	v_exp_f32_e32 v106, v106
	v_exp_f32_e32 v107, v107
	v_add_f32_e32 v105, 1.0, v105
	v_rcp_f32_e32 v104, v104
	v_rcp_f32_e32 v105, v105
	v_add_f32_e32 v106, 1.0, v106
	v_add_f32_e32 v107, 1.0, v107
	v_cndmask_b32_e64 v57, v57, 0, s[0:1]
	v_cndmask_b32_e64 v56, v56, 0, s[0:1]
	v_pk_mul_f32 v[108:109], v[48:49], v[84:85]
	v_rcp_f32_e32 v106, v106
	v_rcp_f32_e32 v107, v107
	v_pk_fma_f32 v[56:57], v[56:57], v[80:81], v[108:109]
	v_pk_fma_f32 v[58:59], v[42:43], v[74:75], v[58:59]
	v_pk_fma_f32 v[56:57], v[40:41], v[72:73], v[56:57]
	v_pk_mul_f32 v[60:61], v[60:61], v[104:105]
	v_pk_add_f32 v[56:57], v[76:77], v[56:57]
	v_pk_add_f32 v[58:59], v[78:79], v[58:59]
	v_pk_mul_f32 v[56:57], v[56:57], v[60:61]
	v_pk_mul_f32 v[60:61], v[62:63], v[106:107]
	v_readlane_b32 s0, v252, 52
	v_pk_mul_f32 v[58:59], v[58:59], v[60:61]
	v_readlane_b32 s1, v252, 53
	v_cvt_pk_bf16_f32 v56, v56, v57
	v_cvt_pk_bf16_f32 v57, v58, v59
	v_mov_b64_e32 v[58:59], s[0:1]
	s_movk_i32 s0, 0x1600
	v_mad_i64_i32 v[58:59], s[0:1], v221, s0, v[58:59]
	v_lshl_add_u64 v[58:59], v[184:185], 1, v[58:59]
	global_store_dwordx2 v[58:59], v[56:57], off offset:8
	s_or_b64 exec, exec, s[18:19]
	s_and_saveexec_b64 s[0:1], s[54:55]
	s_cbranch_execz .LBB0_852
.LBB0_860:
	v_pk_mul_f32 v[106:107], v[44:45], v[92:93]
	v_cndmask_b32_e64 v63, v37, 0, s[14:15]
	v_cndmask_b32_e64 v62, v36, 0, s[14:15]
	v_pk_fma_f32 v[52:53], v[52:53], v[88:89], v[106:107]
	v_pk_mul_f32 v[104:105], v[46:47], v[94:95]
	v_pk_fma_f32 v[52:53], v[62:63], v[68:69], v[52:53]
	v_cndmask_b32_e64 v61, v39, 0, s[14:15]
	v_pk_add_f32 v[52:53], v[64:65], v[52:53]
	v_cndmask_b32_e64 v60, v38, 0, s[14:15]
	v_mul_f32_e32 v62, 0xbfb8aa3b, v52
	v_exp_f32_e32 v62, v62
	v_pk_fma_f32 v[54:55], v[54:55], v[90:91], v[104:105]
	v_pk_mul_f32 v[104:105], v[40:41], v[84:85]
	v_pk_fma_f32 v[54:55], v[60:61], v[70:71], v[54:55]
	v_add_f32_e32 v60, 1.0, v62
	v_pk_mul_f32 v[62:63], v[42:43], v[86:87]
	v_cndmask_b32_e64 v57, v35, 0, s[14:15]
	v_cndmask_b32_e64 v56, v34, 0, s[14:15]
	v_cndmask_b32_e64 v59, v33, 0, s[14:15]
	v_cndmask_b32_e64 v58, v32, 0, s[14:15]
	v_pk_add_f32 v[54:55], v[66:67], v[54:55]
	v_pk_fma_f32 v[50:51], v[50:51], v[82:83], v[62:63]
	v_pk_fma_f32 v[48:49], v[48:49], v[80:81], v[104:105]
	v_mul_f32_e32 v61, 0xbfb8aa3b, v53
	v_exp_f32_e32 v61, v61
	v_pk_fma_f32 v[48:49], v[58:59], v[72:73], v[48:49]
	v_pk_fma_f32 v[50:51], v[56:57], v[74:75], v[50:51]
	v_mul_f32_e32 v57, 0xbfb8aa3b, v54
	v_mul_f32_e32 v58, 0xbfb8aa3b, v55
	v_exp_f32_e32 v57, v57
	v_exp_f32_e32 v58, v58
	v_add_f32_e32 v56, 1.0, v61
	v_rcp_f32_e32 v60, v60
	v_rcp_f32_e32 v61, v56
	v_add_f32_e32 v56, 1.0, v57
	v_add_f32_e32 v57, 1.0, v58
	v_rcp_f32_e32 v56, v56
	v_rcp_f32_e32 v57, v57
	v_pk_add_f32 v[48:49], v[76:77], v[48:49]
	v_pk_mul_f32 v[52:53], v[52:53], v[60:61]
	v_pk_add_f32 v[50:51], v[78:79], v[50:51]
	v_pk_mul_f32 v[48:49], v[48:49], v[52:53]
	v_pk_mul_f32 v[52:53], v[54:55], v[56:57]
	v_readlane_b32 s14, v252, 52
	v_pk_mul_f32 v[50:51], v[50:51], v[52:53]
	v_readlane_b32 s15, v252, 53
	v_cvt_pk_bf16_f32 v48, v48, v49
	v_cvt_pk_bf16_f32 v49, v50, v51
	v_mov_b64_e32 v[50:51], s[14:15]
	s_movk_i32 s14, 0x1600
	v_mad_i64_i32 v[50:51], s[14:15], v153, s14, v[50:51]
	v_lshl_add_u64 v[50:51], v[184:185], 1, v[50:51]
	global_store_dwordx2 v[50:51], v[48:49], off offset:8
	s_or_b64 exec, exec, s[0:1]
	s_and_saveexec_b64 s[0:1], s[56:57]
	s_cbranch_execz .LBB0_853
.LBB0_861:
	v_cndmask_b32_e64 v45, v45, 0, s[4:5]
	v_cndmask_b32_e64 v44, v44, 0, s[4:5]
	v_pk_mul_f32 v[50:51], v[36:37], v[92:93]
	v_cndmask_b32_e64 v47, v47, 0, s[4:5]
	v_pk_fma_f32 v[44:45], v[44:45], v[88:89], v[50:51]
	v_cndmask_b32_e64 v46, v46, 0, s[4:5]
	v_pk_fma_f32 v[44:45], v[28:29], v[68:69], v[44:45]
	v_pk_mul_f32 v[48:49], v[38:39], v[94:95]
	v_pk_add_f32 v[44:45], v[64:65], v[44:45]
	v_pk_fma_f32 v[46:47], v[46:47], v[90:91], v[48:49]
	v_mul_f32_e32 v50, 0xbfb8aa3b, v44
	v_exp_f32_e32 v50, v50
	v_pk_fma_f32 v[46:47], v[30:31], v[70:71], v[46:47]
	v_cndmask_b32_e64 v43, v43, 0, s[4:5]
	v_cndmask_b32_e64 v42, v42, 0, s[4:5]
	v_pk_add_f32 v[46:47], v[66:67], v[46:47]
	v_add_f32_e32 v48, 1.0, v50
	v_pk_mul_f32 v[50:51], v[34:35], v[86:87]
	v_mul_f32_e32 v49, 0xbfb8aa3b, v45
	v_pk_fma_f32 v[42:43], v[42:43], v[82:83], v[50:51]
	v_exp_f32_e32 v49, v49
	v_mul_f32_e32 v50, 0xbfb8aa3b, v46
	v_mul_f32_e32 v51, 0xbfb8aa3b, v47
	v_exp_f32_e32 v50, v50
	v_exp_f32_e32 v51, v51
	v_add_f32_e32 v49, 1.0, v49
	v_rcp_f32_e32 v48, v48
	v_rcp_f32_e32 v49, v49
	v_add_f32_e32 v50, 1.0, v50
	v_add_f32_e32 v51, 1.0, v51
	v_cndmask_b32_e64 v41, v41, 0, s[4:5]
	v_cndmask_b32_e64 v40, v40, 0, s[4:5]
	v_pk_mul_f32 v[52:53], v[32:33], v[84:85]
	v_rcp_f32_e32 v50, v50
	v_rcp_f32_e32 v51, v51
	v_pk_fma_f32 v[40:41], v[40:41], v[80:81], v[52:53]
	v_pk_fma_f32 v[42:43], v[26:27], v[74:75], v[42:43]
	v_pk_fma_f32 v[40:41], v[24:25], v[72:73], v[40:41]
	v_pk_mul_f32 v[44:45], v[44:45], v[48:49]
	v_pk_add_f32 v[40:41], v[76:77], v[40:41]
	v_pk_add_f32 v[42:43], v[78:79], v[42:43]
	v_pk_mul_f32 v[40:41], v[40:41], v[44:45]
	v_pk_mul_f32 v[44:45], v[46:47], v[50:51]
	v_readlane_b32 s4, v252, 52
	v_pk_mul_f32 v[42:43], v[42:43], v[44:45]
	v_readlane_b32 s5, v252, 53
	v_cvt_pk_bf16_f32 v40, v40, v41
	v_cvt_pk_bf16_f32 v41, v42, v43
	v_mov_b64_e32 v[42:43], s[4:5]
	s_movk_i32 s4, 0x1600
	v_mad_i64_i32 v[42:43], s[4:5], v152, s4, v[42:43]
	v_lshl_add_u64 v[42:43], v[184:185], 1, v[42:43]
	global_store_dwordx2 v[42:43], v[40:41], off offset:8
	s_or_b64 exec, exec, s[0:1]
	s_and_saveexec_b64 s[0:1], s[58:59]
	s_cbranch_execz .LBB0_854
.LBB0_862:
	v_pk_mul_f32 v[50:51], v[28:29], v[92:93]
	v_cndmask_b32_e64 v47, v21, 0, s[6:7]
	v_cndmask_b32_e64 v46, v20, 0, s[6:7]
	v_pk_fma_f32 v[36:37], v[36:37], v[88:89], v[50:51]
	v_pk_mul_f32 v[48:49], v[30:31], v[94:95]
	v_pk_fma_f32 v[36:37], v[46:47], v[68:69], v[36:37]
	v_cndmask_b32_e64 v45, v23, 0, s[6:7]
	v_pk_add_f32 v[36:37], v[64:65], v[36:37]
	v_cndmask_b32_e64 v44, v22, 0, s[6:7]
	v_mul_f32_e32 v46, 0xbfb8aa3b, v36
	v_exp_f32_e32 v46, v46
	v_pk_fma_f32 v[38:39], v[38:39], v[90:91], v[48:49]
	v_pk_mul_f32 v[48:49], v[24:25], v[84:85]
	v_pk_fma_f32 v[38:39], v[44:45], v[70:71], v[38:39]
	v_add_f32_e32 v44, 1.0, v46
	v_pk_mul_f32 v[46:47], v[26:27], v[86:87]
	v_cndmask_b32_e64 v41, v19, 0, s[6:7]
	v_cndmask_b32_e64 v40, v18, 0, s[6:7]
	v_cndmask_b32_e64 v43, v17, 0, s[6:7]
	v_cndmask_b32_e64 v42, v16, 0, s[6:7]
	v_pk_add_f32 v[38:39], v[66:67], v[38:39]
	v_pk_fma_f32 v[34:35], v[34:35], v[82:83], v[46:47]
	v_pk_fma_f32 v[32:33], v[32:33], v[80:81], v[48:49]
	v_mul_f32_e32 v45, 0xbfb8aa3b, v37
	v_exp_f32_e32 v45, v45
	v_pk_fma_f32 v[32:33], v[42:43], v[72:73], v[32:33]
	v_pk_fma_f32 v[34:35], v[40:41], v[74:75], v[34:35]
	v_mul_f32_e32 v41, 0xbfb8aa3b, v38
	v_mul_f32_e32 v42, 0xbfb8aa3b, v39
	v_exp_f32_e32 v41, v41
	v_exp_f32_e32 v42, v42
	v_add_f32_e32 v40, 1.0, v45
	v_rcp_f32_e32 v44, v44
	v_rcp_f32_e32 v45, v40
	v_add_f32_e32 v40, 1.0, v41
	v_add_f32_e32 v41, 1.0, v42
	v_rcp_f32_e32 v40, v40
	v_rcp_f32_e32 v41, v41
	v_pk_add_f32 v[32:33], v[76:77], v[32:33]
	v_pk_mul_f32 v[36:37], v[36:37], v[44:45]
	v_pk_add_f32 v[34:35], v[78:79], v[34:35]
	v_pk_mul_f32 v[32:33], v[32:33], v[36:37]
	v_pk_mul_f32 v[36:37], v[38:39], v[40:41]
	v_readlane_b32 s4, v252, 52
	v_pk_mul_f32 v[34:35], v[34:35], v[36:37]
	v_readlane_b32 s5, v252, 53
	v_cvt_pk_bf16_f32 v32, v32, v33
	v_cvt_pk_bf16_f32 v33, v34, v35
	v_mov_b64_e32 v[34:35], s[4:5]
	s_movk_i32 s4, 0x1600
	v_mad_i64_i32 v[34:35], s[4:5], v126, s4, v[34:35]
	v_lshl_add_u64 v[34:35], v[184:185], 1, v[34:35]
	global_store_dwordx2 v[34:35], v[32:33], off offset:8
	s_or_b64 exec, exec, s[0:1]
	s_and_saveexec_b64 s[0:1], s[60:61]
	s_cbranch_execz .LBB0_855
.LBB0_863:
	v_cndmask_b32_e64 v29, v29, 0, s[8:9]
	v_cndmask_b32_e64 v28, v28, 0, s[8:9]
	v_pk_mul_f32 v[34:35], v[20:21], v[92:93]
	v_cndmask_b32_e64 v31, v31, 0, s[8:9]
	v_pk_fma_f32 v[28:29], v[28:29], v[88:89], v[34:35]
	v_cndmask_b32_e64 v30, v30, 0, s[8:9]
	v_pk_fma_f32 v[28:29], v[12:13], v[68:69], v[28:29]
	v_pk_mul_f32 v[32:33], v[22:23], v[94:95]
	v_pk_add_f32 v[28:29], v[64:65], v[28:29]
	v_pk_fma_f32 v[30:31], v[30:31], v[90:91], v[32:33]
	v_mul_f32_e32 v34, 0xbfb8aa3b, v28
	v_exp_f32_e32 v34, v34
	v_pk_fma_f32 v[30:31], v[14:15], v[70:71], v[30:31]
	v_cndmask_b32_e64 v27, v27, 0, s[8:9]
	v_cndmask_b32_e64 v26, v26, 0, s[8:9]
	v_pk_add_f32 v[30:31], v[66:67], v[30:31]
	v_add_f32_e32 v32, 1.0, v34
	v_pk_mul_f32 v[34:35], v[18:19], v[86:87]
	v_mul_f32_e32 v33, 0xbfb8aa3b, v29
	v_pk_fma_f32 v[26:27], v[26:27], v[82:83], v[34:35]
	v_exp_f32_e32 v33, v33
	v_mul_f32_e32 v34, 0xbfb8aa3b, v30
	v_mul_f32_e32 v35, 0xbfb8aa3b, v31
	v_exp_f32_e32 v34, v34
	v_exp_f32_e32 v35, v35
	v_add_f32_e32 v33, 1.0, v33
	v_rcp_f32_e32 v32, v32
	v_rcp_f32_e32 v33, v33
	v_add_f32_e32 v34, 1.0, v34
	v_add_f32_e32 v35, 1.0, v35
	v_cndmask_b32_e64 v25, v25, 0, s[8:9]
	v_cndmask_b32_e64 v24, v24, 0, s[8:9]
	v_pk_mul_f32 v[36:37], v[16:17], v[84:85]
	v_rcp_f32_e32 v34, v34
	v_rcp_f32_e32 v35, v35
	v_pk_fma_f32 v[24:25], v[24:25], v[80:81], v[36:37]
	v_pk_fma_f32 v[26:27], v[6:7], v[74:75], v[26:27]
	v_pk_fma_f32 v[24:25], v[4:5], v[72:73], v[24:25]
	v_pk_mul_f32 v[28:29], v[28:29], v[32:33]
	v_pk_add_f32 v[24:25], v[76:77], v[24:25]
	v_pk_add_f32 v[26:27], v[78:79], v[26:27]
	v_pk_mul_f32 v[24:25], v[24:25], v[28:29]
	v_pk_mul_f32 v[28:29], v[30:31], v[34:35]
	v_readlane_b32 s4, v252, 52
	v_pk_mul_f32 v[26:27], v[26:27], v[28:29]
	v_readlane_b32 s5, v252, 53
	v_cvt_pk_bf16_f32 v24, v24, v25
	v_cvt_pk_bf16_f32 v25, v26, v27
	v_mov_b64_e32 v[26:27], s[4:5]
	s_movk_i32 s4, 0x1600
	v_mad_i64_i32 v[26:27], s[4:5], v124, s4, v[26:27]
	v_lshl_add_u64 v[26:27], v[184:185], 1, v[26:27]
	global_store_dwordx2 v[26:27], v[24:25], off offset:8
	s_or_b64 exec, exec, s[0:1]
	s_and_saveexec_b64 s[0:1], s[62:63]
	s_cbranch_execz .LBB0_856
.LBB0_864:
	v_pk_mul_f32 v[34:35], v[12:13], v[92:93]
	v_cndmask_b32_e64 v31, v9, 0, s[10:11]
	v_cndmask_b32_e64 v30, v8, 0, s[10:11]
	v_pk_fma_f32 v[20:21], v[20:21], v[88:89], v[34:35]
	v_pk_mul_f32 v[32:33], v[14:15], v[94:95]
	v_pk_fma_f32 v[20:21], v[30:31], v[68:69], v[20:21]
	v_cndmask_b32_e64 v29, v11, 0, s[10:11]
	v_pk_add_f32 v[20:21], v[64:65], v[20:21]
	v_cndmask_b32_e64 v28, v10, 0, s[10:11]
	v_mul_f32_e32 v30, 0xbfb8aa3b, v20
	v_exp_f32_e32 v30, v30
	v_pk_fma_f32 v[22:23], v[22:23], v[90:91], v[32:33]
	v_pk_mul_f32 v[32:33], v[4:5], v[84:85]
	v_pk_fma_f32 v[22:23], v[28:29], v[70:71], v[22:23]
	v_add_f32_e32 v28, 1.0, v30
	v_pk_mul_f32 v[30:31], v[6:7], v[86:87]
	v_cndmask_b32_e64 v25, v3, 0, s[10:11]
	v_cndmask_b32_e64 v24, v2, 0, s[10:11]
	v_cndmask_b32_e64 v27, v1, 0, s[10:11]
	v_cndmask_b32_e64 v26, v0, 0, s[10:11]
	v_pk_add_f32 v[22:23], v[66:67], v[22:23]
	v_pk_fma_f32 v[18:19], v[18:19], v[82:83], v[30:31]
	v_pk_fma_f32 v[16:17], v[16:17], v[80:81], v[32:33]
	v_mul_f32_e32 v29, 0xbfb8aa3b, v21
	v_exp_f32_e32 v29, v29
	v_pk_fma_f32 v[16:17], v[26:27], v[72:73], v[16:17]
	v_pk_fma_f32 v[18:19], v[24:25], v[74:75], v[18:19]
	v_mul_f32_e32 v25, 0xbfb8aa3b, v22
	v_mul_f32_e32 v26, 0xbfb8aa3b, v23
	v_exp_f32_e32 v25, v25
	v_exp_f32_e32 v26, v26
	v_add_f32_e32 v24, 1.0, v29
	v_rcp_f32_e32 v28, v28
	v_rcp_f32_e32 v29, v24
	v_add_f32_e32 v24, 1.0, v25
	v_add_f32_e32 v25, 1.0, v26
	v_rcp_f32_e32 v24, v24
	v_rcp_f32_e32 v25, v25
	v_pk_add_f32 v[16:17], v[76:77], v[16:17]
	v_pk_mul_f32 v[20:21], v[20:21], v[28:29]
	v_pk_add_f32 v[18:19], v[78:79], v[18:19]
	v_pk_mul_f32 v[16:17], v[16:17], v[20:21]
	v_pk_mul_f32 v[20:21], v[22:23], v[24:25]
	v_readlane_b32 s4, v252, 52
	v_pk_mul_f32 v[18:19], v[18:19], v[20:21]
	v_readlane_b32 s5, v252, 53
	v_cvt_pk_bf16_f32 v16, v16, v17
	v_cvt_pk_bf16_f32 v17, v18, v19
	v_mov_b64_e32 v[18:19], s[4:5]
	s_movk_i32 s4, 0x1600
	v_mad_i64_i32 v[18:19], s[4:5], v127, s4, v[18:19]
	v_lshl_add_u64 v[18:19], v[184:185], 1, v[18:19]
	global_store_dwordx2 v[18:19], v[16:17], off offset:8
	s_or_b64 exec, exec, s[0:1]
	s_and_saveexec_b64 s[0:1], s[16:17]
	s_cbranch_execz .LBB0_857
.LBB0_865:
	v_cndmask_b32_e64 v13, v13, 0, s[12:13]
	v_cndmask_b32_e64 v12, v12, 0, s[12:13]
	v_pk_mul_f32 v[8:9], v[8:9], v[92:93]
	v_cndmask_b32_e64 v5, v5, 0, s[12:13]
	v_pk_fma_f32 v[8:9], v[12:13], v[88:89], v[8:9]
	v_cndmask_b32_e64 v4, v4, 0, s[12:13]
	v_pk_fma_f32 v[8:9], v[68:69], v[102:103], v[8:9]
	v_pk_mul_f32 v[0:1], v[0:1], v[84:85]
	v_pk_add_f32 v[8:9], v[64:65], v[8:9]
	v_pk_fma_f32 v[0:1], v[4:5], v[80:81], v[0:1]
	v_mul_f32_e32 v12, 0xbfb8aa3b, v8
	v_mul_f32_e32 v4, 0xbfb8aa3b, v9
	v_exp_f32_e32 v12, v12
	v_exp_f32_e32 v4, v4
	v_cndmask_b32_e64 v15, v15, 0, s[12:13]
	v_cndmask_b32_e64 v14, v14, 0, s[12:13]
	v_add_f32_e32 v12, 1.0, v12
	v_add_f32_e32 v4, 1.0, v4
	v_rcp_f32_e32 v12, v12
	v_rcp_f32_e32 v13, v4
	v_pk_mul_f32 v[10:11], v[10:11], v[94:95]
	v_pk_fma_f32 v[0:1], v[72:73], v[100:101], v[0:1]
	v_pk_fma_f32 v[10:11], v[14:15], v[90:91], v[10:11]
	v_pk_add_f32 v[0:1], v[76:77], v[0:1]
	v_pk_mul_f32 v[4:5], v[8:9], v[12:13]
	v_cndmask_b32_e64 v7, v7, 0, s[12:13]
	v_pk_mul_f32 v[0:1], v[0:1], v[4:5]
	v_pk_fma_f32 v[4:5], v[70:71], v[98:99], v[10:11]
	v_cndmask_b32_e64 v6, v6, 0, s[12:13]
	v_pk_mul_f32 v[2:3], v[2:3], v[86:87]
	v_pk_add_f32 v[4:5], v[66:67], v[4:5]
	v_pk_fma_f32 v[2:3], v[6:7], v[82:83], v[2:3]
	v_mul_f32_e32 v6, 0xbfb8aa3b, v4
	v_mul_f32_e32 v7, 0xbfb8aa3b, v5
	v_exp_f32_e32 v6, v6
	v_exp_f32_e32 v7, v7
	v_pk_fma_f32 v[2:3], v[74:75], v[96:97], v[2:3]
	v_readlane_b32 s4, v252, 52
	v_add_f32_e32 v6, 1.0, v6
	v_add_f32_e32 v7, 1.0, v7
	v_rcp_f32_e32 v6, v6
	v_rcp_f32_e32 v7, v7
	v_pk_add_f32 v[2:3], v[78:79], v[2:3]
	v_readlane_b32 s5, v252, 53
	v_cvt_pk_bf16_f32 v0, v0, v1
	v_pk_mul_f32 v[4:5], v[4:5], v[6:7]
	s_nop 0
	v_pk_mul_f32 v[2:3], v[2:3], v[4:5]
	s_nop 0
	v_cvt_pk_bf16_f32 v1, v2, v3
	v_mov_b64_e32 v[2:3], s[4:5]
	s_movk_i32 s4, 0x1600
	v_mad_i64_i32 v[2:3], s[4:5], v125, s4, v[2:3]
	v_lshl_add_u64 v[2:3], v[184:185], 1, v[2:3]
	global_store_dwordx2 v[2:3], v[0:1], off offset:8
	s_or_b64 exec, exec, s[0:1]
	s_and_b64 vcc, exec, s[38:39]
	s_mov_b64 s[0:1], -1
	s_cbranch_vccnz .LBB0_820
